# attention dequeue: own queue goes straight to the atomic, no pre-check load
# baseline (speedup 1.0000x reference)
; __device__ __forceinline__ unsigned xb_xcc_id() { return (unsigned)__builtin_amdgcn_s_getreg((3 << 11) | 20) & 0xFu; }
; __device__ void run_phase(PP p, int ph, u16* lds, float* ssm, int* slot, int rep) {
;     ...
;     const int xq = (int)(xb_xcc_id() & 7u);
;     int* cbase = p->counters + l * 16 + 8 + rep * 64;
;     for (;;) {
;       __syncthreads();
;       if (threadIdx.x == 0) {
;         int got = -1;
;         for (int dq = 0; dq < 8 && got < 0; ++dq) {
;           const int q = (xq + dq) & 7;
;           if (__hip_atomic_load(cbase + q, __ATOMIC_RELAXED, __HIP_MEMORY_SCOPE_AGENT) < 192) {
;             const int it = atomicAdd(cbase + q, 1);
;             if (it < 192) got = q * 256 + it;
;           }
;         }
;         *slot = got;
;       }
;       __syncthreads();
;       const int got = *slot;
;       if (got < 0) break;
.LBB0_425:
	s_add_i32 s40, s56, s42
	s_and_b32 s43, s40, 7
	s_lshl_b32 s40, s43, 2
	s_cmp_eq_u32 s42, 0
	s_cbranch_scc1 .Ldq_own
	s_waitcnt vmcnt(0)
	v_mov_b32_e32 v2, s40
	global_load_dword v2, v2, s[16:17] offset:32 sc1
	s_movk_i32 s44, 0xbf
	s_add_u32 s40, s16, s40
	s_addc_u32 s41, s17, 0
	s_waitcnt vmcnt(0)
	v_cmp_lt_i32_e32 vcc, s44, v2
	s_cbranch_vccnz .LBB0_424
	s_branch .Ldq_atomic
.Ldq_own:
	s_add_u32 s40, s16, s40
	s_addc_u32 s41, s17, 0
.Ldq_atomic:
	global_atomic_add v2, v1, v176, s[40:41] offset:32 sc0
	s_waitcnt vmcnt(0)
	v_lshl_add_u32 v3, s43, 8, v2
	v_cmp_gt_i32_e32 vcc, s23, v2
	s_nop 1
	v_cndmask_b32_e32 v0, v0, v3, vcc
	s_branch .LBB0_424
